# v47 + SwiGLU rstd LDS table refilled when the unit's row panel changes (per-lane 16-load fallback removed)
# baseline (speedup 1.0000x reference)
;     __device__ __forceinline__ void operator()(const f32x4 (&acc)[2][2][4][2], const Unit& u, int wr, int wc, int fr, int fq) const {
;         const int row0 = u.pm * BM + wr * 64 + fr, col0 = u.pn * HALF + wc * 32 + 8 * fq;
;         float rs8[2][4];
;         { f32x4 pa[2][4], pb[2][4];
; #pragma unroll
;           for (int ai = 0; ai < 2; ++ai)
; #pragma unroll
;             for (int m = 0; m < 4; ++m) { const float* p_ = st2 + (size_t)(row0 + ai * HALF + m * 16) * 8; pa[ai][m] = *(const f32x4*)p_; pb[ai][m] = *(const f32x4*)(p_ + 4); }
;           __builtin_amdgcn_sched_barrier(0);
; #pragma unroll
;           for (int ai = 0; ai < 2; ++ai)
; #pragma unroll
;             for (int m = 0; m < 4; ++m) { const f32x4 t_ = pa[ai][m] + pb[ai][m]; rs8[ai][m] = __builtin_amdgcn_rsqf(((t_[0] + t_[1]) + (t_[2] + t_[3])) * (1.0f / (float)D) + 1e-6f); }
;           __builtin_amdgcn_sched_barrier(0); }
.Lmy_sw_fast:
	v_lshlrev_b32_e32 v162, 2, v158
	v_add_u32_e32 v162, 0x21800, v162
	ds_read_b32 v147, v162
	ds_read_b32 v149, v162 offset:64
	ds_read_b32 v151, v162 offset:128
	ds_read_b32 v153, v162 offset:192
	ds_read_b32 v155, v162 offset:512
	ds_read_b32 v157, v162 offset:576
	ds_read_b32 v145, v162 offset:640
	ds_read_b32 v143, v162 offset:704
	v_or_b32_e32 v154, 16, v156
	v_or_b32_e32 v152, 32, v156
	v_or_b32_e32 v150, 48, v156
	v_add_u32_e32 v148, 0x80, v156
	v_add_u32_e32 v146, 0x90, v156
	v_add_u32_e32 v144, 0xa0, v156
	v_add_u32_e32 v142, 0xb0, v156
	s_waitcnt lgkmcnt(0)
	s_branch .Lmy_sw_join
.Lmy_sw_slow:
	v_cmp_gt_u32_e32 vcc, 0x100, v0
	s_and_saveexec_b64 s[100:101], vcc
	s_cbranch_execz .Lmy_rsfill2_done
	v_lshl_add_u32 v162, s54, 8, v0
	v_lshlrev_b32_e32 v162, 5, v162
	global_load_dwordx4 v[164:167], v162, s[14:15]
	global_load_dwordx4 v[168:171], v162, s[14:15] offset:16
	v_lshlrev_b32_e32 v163, 2, v0
	v_add_u32_e32 v163, 0x21800, v163
	s_waitcnt vmcnt(0)
	v_add_f32_e32 v164, v164, v168
	v_add_f32_e32 v165, v165, v169
	v_add_f32_e32 v166, v166, v170
	v_add_f32_e32 v167, v167, v171
	v_add_f32_e32 v164, v165, v164
	v_add_f32_e32 v166, v166, v167
	v_add_f32_e32 v164, v164, v166
	v_fmamk_f32 v164, v164, 0x3a000000, v1
	v_rsq_f32_e32 v164, v164
	s_nop 0
	ds_write_b32 v163, v164
.Lmy_rsfill2_done:
	s_or_b64 exec, exec, s[100:101]
	s_mov_b32 s100, s54
	s_waitcnt lgkmcnt(0)
	s_barrier
	s_branch .Lmy_sw_fast

; #define PG8_STAGE(bufoff, gbase, voff) do { _Pragma("unroll") for (int _i = 0; _i < 2; ++_i) \
;         __builtin_amdgcn_global_load_lds((const unsigned*)((const char*)(gbase) + (voff)[_i]), (LAS unsigned*)(lds + (bufoff) + ldsw + _i * 8192), 16, 0, 0); } while (0)
; #define PG8_WAIT_V(n) asm volatile("s_waitcnt vmcnt(" #n ")" ::: "memory")
; #define PG8_BAR __builtin_amdgcn_s_barrier()
; template <class Epi, class Sched>
; __device__ __forceinline__ void gemm_phase(LAS unsigned char* lds, const Gemm g, const Sched& S, const Epi& E) {
;     ...
;     f32x4 acc[2][2][4][2];
; #pragma unroll
;     for (int a = 0; a < 2; ++a)
; #pragma unroll
;         for (int b = 0; b < 2; ++b)
; #pragma unroll
;             for (int m = 0; m < 4; ++m)
; #pragma unroll
;                 for (int n = 0; n < 2; ++n) acc[a][b][m][n] = (f32x4){0.f, 0.f, 0.f, 0.f};
;     bf16x8 At[4][2], B0[2][2], B1[2][2];
;     const char* cA = (const char*)g.A + (size_t)cur.pm * tstepA + (size_t)cur.ka * 2; const char* cB = (const char*)g.Bt + (size_t)cur.pn * tstepB;
;     S.a_ready(cur);
;     PG8_STAGE(PG8_SB(0, 0), cB, voffB); PG8_STAGE(PG8_SB(0, 1), cB + hstepB, voffB); PG8_STAGE(PG8_SA(0, 0), cA, voffA); PG8_STAGE(PG8_SA(0, 1), cA + hstepA, voffA);
;     if (wr == 1) PG8_BAR;
;     PG8_WAIT_V(2); PG8_BAR;
;     PG8_STAGE(PG8_SB(1, 0), cB + kstep, voffB); PG8_STAGE(PG8_SA(1, 0), cA + kstep, voffA); PG8_STAGE(PG8_SB(1, 1), cB + hstepB + kstep, voffB);
;     PG8_WAIT_V(6); PG8_BAR;
.LBB0_267:
	v_lshl_add_u64 v[14:15], s[24:25], 0, v[4:5]
	v_mov_b32_e32 v3, v5
	v_and_b32_e32 v142, 15, v143
	v_and_b32_e32 v22, 48, v143
	v_lshlrev_b32_e32 v23, 2, v143
	v_lshl_add_u64 v[16:17], s[24:25], 0, v[2:3]
	s_and_b32 s48, s44, 3
	v_lshl_or_b32 v22, v142, 6, v22
	s_lshl_b32 s4, s47, 13
	v_and_b32_e32 v23, 32, v23
	s_add_i32 m0, s50, 0x18000
	v_lshl_add_u64 v[14:15], v[14:15], 0, s[36:37]
	v_lshl_add_u64 v[18:19], s[20:21], 0, v[4:5]
	v_bitop3_b32 v24, v22, s4, v23 bitop3:0xde
	s_lshl_b32 s4, s48, 12
	s_waitcnt vmcnt(2)
	s_barrier
	global_load_lds_dwordx4 v[14:15], off
	v_lshl_add_u64 v[14:15], v[16:17], 0, s[36:37]
	s_add_i32 m0, s50, 0x1a000
	s_add_i32 s54, s50, 0x8000
	s_add_i32 s55, s50, 0xa000
	v_lshl_add_u64 v[20:21], s[20:21], 0, v[2:3]
	v_bitop3_b32 v144, v22, s4, v23 bitop3:0xde
	global_load_lds_dwordx4 v[14:15], off
	v_lshl_add_u64 v[14:15], v[18:19], 0, s[36:37]
	s_mov_b32 m0, s54
	s_add_u32 s4, s24, 0x158080
	global_load_lds_dwordx4 v[14:15], off
	v_lshl_add_u64 v[14:15], v[20:21], 0, s[36:37]
	s_mov_b32 m0, s55
	s_addc_u32 s5, s25, 0
	global_load_lds_dwordx4 v[14:15], off
	s_add_i32 m0, s50, 0x1c000
	v_lshl_add_u64 v[14:15], s[4:5], 0, v[4:5]
	global_load_lds_dwordx4 v[14:15], off
	v_lshl_add_u64 v[14:15], s[4:5], 0, v[2:3]
	s_add_i32 m0, s50, 0x1e000
	s_movk_i32 s10, 0x1580
	global_load_lds_dwordx4 v[14:15], off
	v_lshrrev_b32_e32 v11, 1, v11
	v_mul_lo_u32 v10, v10, s10
	s_mov_b32 s22, 0x15800
	v_mad_u64_u32 v[10:11], s[4:5], v11, s22, v[10:11]
	v_or_b32_e32 v10, v10, v12
	v_add_lshl_u32 v134, v10, v13, 1
	v_lshrrev_b32_e32 v10, 1, v6
	v_mul_lo_u32 v6, v7, s10
	v_mad_u64_u32 v[6:7], s[4:5], v10, s22, v[6:7]
	s_waitcnt vmcnt(6)
	v_or_b32_e32 v6, v6, v8
	s_cmpk_lt_u32 s45, 0x100
	v_add_lshl_u32 v136, v6, v9, 1
	v_mov_b32_e32 v6, 0
	v_readlane_b32 s4, v254, 13
	s_cselect_b64 s[18:19], -1, 0
	v_mov_b32_e32 v135, v5
	v_mov_b32_e32 v137, v5
	s_mov_b32 s59, 0
	v_add_u32_e32 v145, 0, v24
	s_mov_b32 s10, s4
	v_readlane_b32 s46, v253, 61
	v_mov_b32_e32 v7, v6
	v_mov_b32_e32 v8, v6
	v_mov_b32_e32 v9, v6
	v_mov_b32_e32 v10, v6
	v_mov_b32_e32 v11, v6
	v_mov_b32_e32 v12, v6
	v_mov_b32_e32 v13, v6
	v_mov_b32_e32 v14, v6
	v_mov_b32_e32 v15, v6
	v_mov_b32_e32 v16, v6
	v_mov_b32_e32 v17, v6
	v_mov_b32_e32 v18, v6
	v_mov_b32_e32 v19, v6
	v_mov_b32_e32 v20, v6
	v_mov_b32_e32 v21, v6
	v_mov_b32_e32 v22, v6
	v_mov_b32_e32 v23, v6
	v_mov_b32_e32 v24, v6
	v_mov_b32_e32 v25, v6
	v_mov_b32_e32 v30, v6
	v_mov_b32_e32 v31, v6
	v_mov_b32_e32 v32, v6
	v_mov_b32_e32 v33, v6
	v_mov_b32_e32 v38, v6
	v_mov_b32_e32 v39, v6
	v_mov_b32_e32 v40, v6
	v_mov_b32_e32 v41, v6
	v_mov_b32_e32 v46, v6
	v_mov_b32_e32 v47, v6
	v_mov_b32_e32 v48, v6
	v_mov_b32_e32 v49, v6
	v_mov_b32_e32 v26, v6
	v_mov_b32_e32 v27, v6
	v_mov_b32_e32 v28, v6
	v_mov_b32_e32 v29, v6
	v_mov_b32_e32 v34, v6
	v_mov_b32_e32 v35, v6
	v_mov_b32_e32 v36, v6
	v_mov_b32_e32 v37, v6
	v_mov_b32_e32 v42, v6
	v_mov_b32_e32 v43, v6
	v_mov_b32_e32 v44, v6
	v_mov_b32_e32 v45, v6
	v_mov_b32_e32 v50, v6
	v_mov_b32_e32 v51, v6
	v_mov_b32_e32 v52, v6
	v_mov_b32_e32 v53, v6
	v_mov_b32_e32 v54, v6
	v_mov_b32_e32 v55, v6
	v_mov_b32_e32 v56, v6
	v_mov_b32_e32 v57, v6
	v_mov_b32_e32 v58, v6
	v_mov_b32_e32 v59, v6
	v_mov_b32_e32 v60, v6
	v_mov_b32_e32 v61, v6
	v_mov_b32_e32 v62, v6
	v_mov_b32_e32 v63, v6
	v_mov_b32_e32 v64, v6
	v_mov_b32_e32 v65, v6
	v_mov_b32_e32 v66, v6
	v_mov_b32_e32 v67, v6
	v_mov_b32_e32 v68, v6
	v_mov_b32_e32 v69, v6
	v_mov_b32_e32 v70, v6
	v_mov_b32_e32 v71, v6
	v_mov_b32_e32 v72, v6
	v_mov_b32_e32 v73, v6
	v_mov_b32_e32 v74, v6
	v_mov_b32_e32 v75, v6
	v_mov_b32_e32 v76, v6
	v_mov_b32_e32 v77, v6
	v_mov_b32_e32 v78, v6
	v_mov_b32_e32 v79, v6
	v_mov_b32_e32 v80, v6
	v_mov_b32_e32 v81, v6
	v_mov_b32_e32 v82, v6
	v_mov_b32_e32 v83, v6
	v_mov_b32_e32 v84, v6
	v_mov_b32_e32 v85, v6
	v_mov_b32_e32 v86, v6
	v_mov_b32_e32 v87, v6
	v_mov_b32_e32 v88, v6
	v_mov_b32_e32 v89, v6
	v_mov_b32_e32 v94, v6
	v_mov_b32_e32 v95, v6
	v_mov_b32_e32 v96, v6
	v_mov_b32_e32 v97, v6
	v_mov_b32_e32 v102, v6
	v_mov_b32_e32 v103, v6
	v_mov_b32_e32 v104, v6
	v_mov_b32_e32 v105, v6
	v_mov_b32_e32 v114, v6
	v_mov_b32_e32 v115, v6
	v_mov_b32_e32 v116, v6
	v_mov_b32_e32 v117, v6
	v_mov_b32_e32 v90, v6
	v_mov_b32_e32 v91, v6
	v_mov_b32_e32 v92, v6
	v_mov_b32_e32 v93, v6
	v_mov_b32_e32 v98, v6
	v_mov_b32_e32 v99, v6
	v_mov_b32_e32 v100, v6
	v_mov_b32_e32 v101, v6
	v_mov_b32_e32 v106, v6
	v_mov_b32_e32 v107, v6
	v_mov_b32_e32 v108, v6
	v_mov_b32_e32 v109, v6
	v_mov_b32_e32 v110, v6
	v_mov_b32_e32 v111, v6
	v_mov_b32_e32 v112, v6
	v_mov_b32_e32 v113, v6
	v_mov_b32_e32 v118, v6
	v_mov_b32_e32 v119, v6
	v_mov_b32_e32 v120, v6
	v_mov_b32_e32 v121, v6
	v_mov_b32_e32 v122, v6
	v_mov_b32_e32 v123, v6
	v_mov_b32_e32 v124, v6
	v_mov_b32_e32 v125, v6
	v_mov_b32_e32 v126, v6
	v_mov_b32_e32 v127, v6
	v_mov_b32_e32 v128, v6
	v_mov_b32_e32 v129, v6
	v_mov_b32_e32 v130, v6
	v_mov_b32_e32 v131, v6
	v_mov_b32_e32 v132, v6
	v_mov_b32_e32 v133, v6
	s_barrier
	s_branch .LBB0_270
	s_nop 0
	s_nop 0
	s_nop 0
	s_nop 0
	s_nop 0
	s_nop 0
	s_nop 0
	s_nop 0
	s_nop 0
	s_nop 0
	s_nop 0
	s_nop 0
	s_nop 0
	s_nop 0
	s_nop 0
	s_nop 0
	s_nop 0
	s_nop 0
	s_nop 0
	s_nop 0
	s_nop 0
	s_nop 0
	s_nop 0
	s_nop 0
	s_nop 0
	s_nop 0
	s_nop 0
	s_nop 0
	s_nop 0
	s_nop 0
	s_nop 0
	s_nop 0
	s_nop 0
	s_nop 0
	s_nop 0
